# HGRN output stage: inter-chunk state matmul loop regenerated with LDS operand reads issued one group ahead into alternate register sets and in-place packed FMA accumulators
# speedup vs baseline: 1.0022x; 1.0022x over previous
; DI float ex2(float x) { return __builtin_amdgcn_exp2f(x); }
; DI void hgrn_h3(const Params& p, int l, int item, char* lds) {
;     ...
; #pragma unroll
;     for (int j = 0; j < 16; ++j) if (sq + 4 * j > t) at[j] = 0.f;
;   }
;   __syncthreads();
;   { const int t = tid >> 2, d0 = (tid & 3) * 16, sq = tid & 3;
; #pragma unroll
;     for (int j = 0; j < 16; ++j) QS[t * HP + d0 + j] *= ex2(B2[t * HP + d0 + j]);
; #pragma unroll
;     for (int j = 0; j < 16; ++j) LK[t * HP + sq + 4 * j] = at[j]; }
;   __syncthreads();
;   { const float* sp = p.U + (size_t)item * 4096;
; #pragma unroll
;     for (int i = 0; i < 4; ++i) { const int i4 = tid + 256 * i, d = i4 >> 4, e0 = (i4 & 15) * 4; *(f32x4*)(B2 + d * HP + e0) = *(const f32x4*)(sp + d * 64 + e0); } }
;   __syncthreads();
;   const int tblk = tid >> 4, eblk = tid & 15;
;   float ao[4][4];
; #pragma unroll
;   for (int i = 0; i < 4; ++i)
; #pragma unroll
;     for (int j = 0; j < 4; ++j) ao[i][j] = 0.f;
;   for (int d4 = 0; d4 < 16; ++d4) {
;     float a[4][4], sv[4][4];
; #pragma unroll
;     for (int i = 0; i < 4; ++i) { const f32x4 x = *(const f32x4*)(QS + (4 * tblk + i) * HP + 4 * d4); a[i][0] = x.x; a[i][1] = x.y; a[i][2] = x.z; a[i][3] = x.w; }
; #pragma unroll
;     for (int dd = 0; dd < 4; ++dd) { const f32x4 x = *(const f32x4*)(B2 + (4 * d4 + dd) * HP + 4 * eblk); sv[dd][0] = x.x; sv[dd][1] = x.y; sv[dd][2] = x.z; sv[dd][3] = x.w; }
.LBB0_643:
	v_cmp_le_u32_e32 vcc, v27, v33
	v_or_b32_e32 v16, 4, v27
	v_lshl_add_u32 v53, v27, 6, v34
	v_cndmask_b32_e32 v28, 0, v28, vcc
	v_cmp_le_u32_e32 vcc, v16, v33
	v_or_b32_e32 v16, 8, v27
	s_nop 0
	v_cndmask_b32_e32 v29, 0, v29, vcc
	v_cmp_le_u32_e32 vcc, v16, v33
	s_barrier
	s_nop 0
	v_cndmask_b32_e32 v35, 0, v2, vcc
	v_or_b32_e32 v2, 12, v27
	v_cmp_le_u32_e32 vcc, v2, v33
	v_or_b32_e32 v2, 16, v27
	v_or_b32_e32 v52, 60, v27
	v_cndmask_b32_e32 v36, 0, v3, vcc
	v_cmp_le_u32_e32 vcc, v2, v33
	v_or_b32_e32 v2, 20, v27
	v_readlane_b32 s44, v253, 0
	v_cndmask_b32_e32 v37, 0, v4, vcc
	v_cmp_le_u32_e32 vcc, v2, v33
	v_or_b32_e32 v2, 24, v27
	v_readlane_b32 s45, v253, 1
	v_cndmask_b32_e32 v38, 0, v5, vcc
	v_cmp_le_u32_e32 vcc, v2, v33
	v_or_b32_e32 v2, 28, v27
	s_mov_b32 s0, 0
	v_cndmask_b32_e32 v39, 0, v6, vcc
	v_cmp_le_u32_e32 vcc, v2, v33
	v_or_b32_e32 v2, 32, v27
	v_readlane_b32 s46, v253, 2
	v_cndmask_b32_e32 v40, 0, v7, vcc
	v_cmp_le_u32_e32 vcc, v2, v33
	v_or_b32_e32 v2, 36, v27
	v_readlane_b32 s47, v253, 3
	v_cndmask_b32_e32 v41, 0, v8, vcc
	v_cmp_le_u32_e32 vcc, v2, v33
	v_or_b32_e32 v2, 40, v27
	s_nop 0
	v_cndmask_b32_e32 v42, 0, v9, vcc
	v_cmp_le_u32_e32 vcc, v2, v33
	v_or_b32_e32 v2, 44, v27
	s_nop 0
	v_cndmask_b32_e32 v43, 0, v10, vcc
	v_cmp_le_u32_e32 vcc, v2, v33
	v_or_b32_e32 v2, 48, v27
	s_nop 0
	v_cndmask_b32_e32 v49, 0, v11, vcc
	v_cmp_le_u32_e32 vcc, v2, v33
	v_or_b32_e32 v2, 52, v27
	s_nop 0
	v_cndmask_b32_e32 v50, 0, v12, vcc
	v_cmp_le_u32_e32 vcc, v2, v33
	v_or_b32_e32 v2, 56, v27
	s_nop 0
	v_cndmask_b32_e32 v51, 0, v13, vcc
	v_cmp_le_u32_e32 vcc, v2, v33
	ds_read_b128 v[2:5], v53 offset:17408
	ds_read_b128 v[6:9], v53
	ds_read_b128 v[10:13], v53 offset:16
	ds_read_b128 v[16:19], v53 offset:32
	ds_read_b128 v[20:23], v53 offset:48
	v_cndmask_b32_e32 v14, 0, v14, vcc
	v_cmp_le_u32_e32 vcc, v52, v33
	s_waitcnt lgkmcnt(4)
	v_exp_f32_e32 v2, v2
	v_exp_f32_e32 v3, v3
	v_exp_f32_e32 v4, v4
	v_exp_f32_e32 v5, v5
	s_waitcnt lgkmcnt(3)
	v_pk_mul_f32 v[2:3], v[6:7], v[2:3]
	v_pk_mul_f32 v[4:5], v[8:9], v[4:5]
	ds_write_b128 v53, v[2:5]
	ds_read_b128 v[2:5], v53 offset:17424
	v_mov_b32_e32 v9, v1
	s_waitcnt lgkmcnt(0)
	v_exp_f32_e32 v2, v2
	v_exp_f32_e32 v3, v3
	v_exp_f32_e32 v4, v4
	v_exp_f32_e32 v5, v5
	v_pk_mul_f32 v[2:3], v[10:11], v[2:3]
	v_pk_mul_f32 v[4:5], v[12:13], v[4:5]
	ds_write_b128 v53, v[2:5] offset:16
	ds_read_b128 v[2:5], v53 offset:17440
	v_mov_b32_e32 v13, v1
	s_waitcnt lgkmcnt(0)
	v_exp_f32_e32 v2, v2
	v_exp_f32_e32 v3, v3
	v_exp_f32_e32 v4, v4
	v_exp_f32_e32 v5, v5
	v_pk_mul_f32 v[2:3], v[16:17], v[2:3]
	v_pk_mul_f32 v[4:5], v[18:19], v[4:5]
	ds_write_b128 v53, v[2:5] offset:32
	ds_read_b128 v[2:5], v53 offset:17456
	s_waitcnt lgkmcnt(0)
	v_exp_f32_e32 v2, v2
	v_exp_f32_e32 v3, v3
	v_exp_f32_e32 v4, v4
	v_exp_f32_e32 v5, v5
	v_pk_mul_f32 v[2:3], v[20:21], v[2:3]
	v_pk_mul_f32 v[4:5], v[22:23], v[4:5]
	ds_write_b128 v53, v[2:5] offset:48
	v_lshl_add_u32 v3, v27, 2, v34
	v_cndmask_b32_e32 v2, 0, v15, vcc
	v_add_u32_e32 v3, 0x8800, v3
	v_ashrrev_i32_e32 v27, 31, v26
	v_lshlrev_b32_e32 v4, 2, v32
	ds_write2_b32 v3, v28, v29 offset1:4
	ds_write2_b32 v3, v35, v36 offset0:8 offset1:12
	ds_write2_b32 v3, v37, v38 offset0:16 offset1:20
	ds_write2_b32 v3, v39, v40 offset0:24 offset1:28
	ds_write2_b32 v3, v41, v42 offset0:32 offset1:36
	ds_write2_b32 v3, v43, v49 offset0:40 offset1:44
	ds_write2_b32 v3, v50, v51 offset0:48 offset1:52
	ds_write2_b32 v3, v14, v2 offset0:56 offset1:60
	v_lshlrev_b64 v[2:3], 14, v[26:27]
	v_and_b32_e32 v14, 60, v4
	v_lshl_add_u64 v[2:3], s[44:45], 0, v[2:3]
	v_lshlrev_b32_e32 v8, 2, v14
	v_lshl_add_u64 v[10:11], v[2:3], 0, v[8:9]
	v_lshrrev_b32_sdwa v2, v243, v32 dst_sel:DWORD dst_unused:UNUSED_PAD src0_sel:DWORD src1_sel:BYTE_0
	v_lshlrev_b32_e32 v12, 8, v2
	v_lshl_add_u64 v[4:5], v[10:11], 0, v[12:13]
	s_waitcnt lgkmcnt(0)
	s_barrier
	global_load_dwordx4 v[4:7], v[4:5], off
	v_mul_u32_u24_e32 v3, 0x110, v2
	v_add3_u32 v8, v250, v8, v3
	s_waitcnt vmcnt(0)
	ds_write_b128 v8, v[4:7] offset:17408
	v_or_b32_e32 v4, 0x1000, v12
	v_mov_b32_e32 v5, v1
	v_lshl_add_u64 v[4:5], v[10:11], 0, v[4:5]
	global_load_dwordx4 v[4:7], v[4:5], off
	s_waitcnt vmcnt(0)
	ds_write_b128 v8, v[4:7] offset:21760
	v_or_b32_e32 v4, 0x2000, v12
	v_mov_b32_e32 v5, v1
	v_lshl_add_u64 v[4:5], v[10:11], 0, v[4:5]
	global_load_dwordx4 v[4:7], v[4:5], off
	s_waitcnt vmcnt(0)
	ds_write_b128 v8, v[4:7] offset:26112
	v_or_b32_e32 v4, 0x3000, v12
	v_mov_b32_e32 v5, v1
	v_lshl_add_u64 v[4:5], v[10:11], 0, v[4:5]
	global_load_dwordx4 v[4:7], v[4:5], off
	s_waitcnt vmcnt(0)
	ds_write_b128 v8, v[4:7] offset:30464
	v_lshlrev_b32_e32 v4, 4, v32
	v_and_b32_e32 v4, 0xf0, v4
	v_mov_b32_e32 v6, 0
	v_lshl_add_u32 v5, v3, 2, v250
	v_add_u32_e32 v15, v47, v4
	v_mov_b32_e32 v7, v6
	v_mov_b32_e32 v8, v6
	v_mov_b32_e32 v9, v6
	v_mov_b32_e32 v10, v6
	v_mov_b32_e32 v11, v6
	v_mov_b32_e32 v12, v6
	v_mov_b32_e32 v13, v6
	v_mov_b32_e32 v18, v6
	v_mov_b32_e32 v19, v6
	v_mov_b32_e32 v22, v6
	v_mov_b32_e32 v23, v6
	v_mov_b32_e32 v26, v6
	v_mov_b32_e32 v27, v6
	v_mov_b32_e32 v28, v6
	v_mov_b32_e32 v29, v6
	s_waitcnt lgkmcnt(0)
	s_barrier
	v_add_u32_e32 v49, s0, v5
	ds_read_b128 v[76:79], v49
	ds_read_b128 v[80:83], v49 offset:272
	ds_read_b128 v[84:87], v49 offset:544
	ds_read_b128 v[88:91], v49 offset:816
	ds_read_b128 v[92:95], v15
	ds_read_b128 v[96:99], v15 offset:272
	ds_read_b128 v[100:103], v15 offset:544
	ds_read_b128 v[104:107], v15 offset:816
; DI void hgrn_h3(const Params& p, int l, int item, char* lds) {
;     ...
;   for (int d4 = 0; d4 < 16; ++d4) {
;     float a[4][4], sv[4][4];
; #pragma unroll
;     for (int i = 0; i < 4; ++i) { const f32x4 x = *(const f32x4*)(QS + (4 * tblk + i) * HP + 4 * d4); a[i][0] = x.x; a[i][1] = x.y; a[i][2] = x.z; a[i][3] = x.w; }
; #pragma unroll
;     for (int dd = 0; dd < 4; ++dd) { const f32x4 x = *(const f32x4*)(B2 + (4 * d4 + dd) * HP + 4 * eblk); sv[dd][0] = x.x; sv[dd][1] = x.y; sv[dd][2] = x.z; sv[dd][3] = x.w; }
; #pragma unroll
;     for (int i = 0; i < 4; ++i)
; #pragma unroll
;       for (int dd = 0; dd < 4; ++dd)
; #pragma unroll
;         for (int j = 0; j < 4; ++j) ao[i][j] += a[i][dd] * sv[dd][j];
;   }
.LBB0_644:
	s_waitcnt lgkmcnt(0)
	ds_read_b128 v[108:111], v49 offset:16
	ds_read_b128 v[112:115], v49 offset:288
	ds_read_b128 v[116:119], v49 offset:560
	ds_read_b128 v[120:123], v49 offset:832
	ds_read_b128 v[124:127], v15 offset:1088
	ds_read_b128 v[128:131], v15 offset:1360
	ds_read_b128 v[132:135], v15 offset:1632
	ds_read_b128 v[136:139], v15 offset:1904
	v_pk_fma_f32 v[28:29], v[76:77], v[92:93], v[28:29] op_sel_hi:[0,1,1]
	v_pk_fma_f32 v[26:27], v[76:77], v[94:95], v[26:27] op_sel_hi:[0,1,1]
	v_pk_fma_f32 v[22:23], v[80:81], v[92:93], v[22:23] op_sel_hi:[0,1,1]
	v_pk_fma_f32 v[18:19], v[80:81], v[94:95], v[18:19] op_sel_hi:[0,1,1]
	v_pk_fma_f32 v[12:13], v[84:85], v[92:93], v[12:13] op_sel_hi:[0,1,1]
	v_pk_fma_f32 v[10:11], v[84:85], v[94:95], v[10:11] op_sel_hi:[0,1,1]
	v_pk_fma_f32 v[8:9], v[88:89], v[92:93], v[8:9] op_sel_hi:[0,1,1]
	v_pk_fma_f32 v[6:7], v[88:89], v[94:95], v[6:7] op_sel_hi:[0,1,1]
	v_pk_fma_f32 v[28:29], v[76:77], v[96:97], v[28:29] op_sel:[1,0,0]
	v_pk_fma_f32 v[26:27], v[76:77], v[98:99], v[26:27] op_sel:[1,0,0]
	v_pk_fma_f32 v[22:23], v[80:81], v[96:97], v[22:23] op_sel:[1,0,0]
	v_pk_fma_f32 v[18:19], v[80:81], v[98:99], v[18:19] op_sel:[1,0,0]
	v_pk_fma_f32 v[12:13], v[84:85], v[96:97], v[12:13] op_sel:[1,0,0]
	v_pk_fma_f32 v[10:11], v[84:85], v[98:99], v[10:11] op_sel:[1,0,0]
	v_pk_fma_f32 v[8:9], v[88:89], v[96:97], v[8:9] op_sel:[1,0,0]
	v_pk_fma_f32 v[6:7], v[88:89], v[98:99], v[6:7] op_sel:[1,0,0]
	v_pk_fma_f32 v[28:29], v[78:79], v[100:101], v[28:29] op_sel_hi:[0,1,1]
	v_pk_fma_f32 v[26:27], v[78:79], v[102:103], v[26:27] op_sel_hi:[0,1,1]
	v_pk_fma_f32 v[22:23], v[82:83], v[100:101], v[22:23] op_sel_hi:[0,1,1]
	v_pk_fma_f32 v[18:19], v[82:83], v[102:103], v[18:19] op_sel_hi:[0,1,1]
	v_pk_fma_f32 v[12:13], v[86:87], v[100:101], v[12:13] op_sel_hi:[0,1,1]
	v_pk_fma_f32 v[10:11], v[86:87], v[102:103], v[10:11] op_sel_hi:[0,1,1]
	v_pk_fma_f32 v[8:9], v[90:91], v[100:101], v[8:9] op_sel_hi:[0,1,1]
	v_pk_fma_f32 v[6:7], v[90:91], v[102:103], v[6:7] op_sel_hi:[0,1,1]
	v_pk_fma_f32 v[28:29], v[78:79], v[104:105], v[28:29] op_sel:[1,0,0]
	v_pk_fma_f32 v[26:27], v[78:79], v[106:107], v[26:27] op_sel:[1,0,0]
	v_pk_fma_f32 v[22:23], v[82:83], v[104:105], v[22:23] op_sel:[1,0,0]
	v_pk_fma_f32 v[18:19], v[82:83], v[106:107], v[18:19] op_sel:[1,0,0]
	v_pk_fma_f32 v[12:13], v[86:87], v[104:105], v[12:13] op_sel:[1,0,0]
	v_pk_fma_f32 v[10:11], v[86:87], v[106:107], v[10:11] op_sel:[1,0,0]
	v_pk_fma_f32 v[8:9], v[90:91], v[104:105], v[8:9] op_sel:[1,0,0]
	v_pk_fma_f32 v[6:7], v[90:91], v[106:107], v[6:7] op_sel:[1,0,0]
	s_add_i32 s0, s0, 32
	s_waitcnt lgkmcnt(0)
	ds_read_b128 v[76:79], v49 offset:32
	ds_read_b128 v[80:83], v49 offset:304
	ds_read_b128 v[84:87], v49 offset:576
	ds_read_b128 v[88:91], v49 offset:848
	ds_read_b128 v[92:95], v15 offset:2176
	ds_read_b128 v[96:99], v15 offset:2448
	ds_read_b128 v[100:103], v15 offset:2720
	ds_read_b128 v[104:107], v15 offset:2992
	v_pk_fma_f32 v[28:29], v[108:109], v[124:125], v[28:29] op_sel_hi:[0,1,1]
	v_pk_fma_f32 v[26:27], v[108:109], v[126:127], v[26:27] op_sel_hi:[0,1,1]
	v_pk_fma_f32 v[22:23], v[112:113], v[124:125], v[22:23] op_sel_hi:[0,1,1]
	v_pk_fma_f32 v[18:19], v[112:113], v[126:127], v[18:19] op_sel_hi:[0,1,1]
	v_pk_fma_f32 v[12:13], v[116:117], v[124:125], v[12:13] op_sel_hi:[0,1,1]
	v_pk_fma_f32 v[10:11], v[116:117], v[126:127], v[10:11] op_sel_hi:[0,1,1]
	v_pk_fma_f32 v[8:9], v[120:121], v[124:125], v[8:9] op_sel_hi:[0,1,1]
	v_pk_fma_f32 v[6:7], v[120:121], v[126:127], v[6:7] op_sel_hi:[0,1,1]
	v_pk_fma_f32 v[28:29], v[108:109], v[128:129], v[28:29] op_sel:[1,0,0]
	v_pk_fma_f32 v[26:27], v[108:109], v[130:131], v[26:27] op_sel:[1,0,0]
	v_pk_fma_f32 v[22:23], v[112:113], v[128:129], v[22:23] op_sel:[1,0,0]
	v_pk_fma_f32 v[18:19], v[112:113], v[130:131], v[18:19] op_sel:[1,0,0]
	v_pk_fma_f32 v[12:13], v[116:117], v[128:129], v[12:13] op_sel:[1,0,0]
	v_pk_fma_f32 v[10:11], v[116:117], v[130:131], v[10:11] op_sel:[1,0,0]
	v_pk_fma_f32 v[8:9], v[120:121], v[128:129], v[8:9] op_sel:[1,0,0]
	v_pk_fma_f32 v[6:7], v[120:121], v[130:131], v[6:7] op_sel:[1,0,0]
	v_pk_fma_f32 v[28:29], v[110:111], v[132:133], v[28:29] op_sel_hi:[0,1,1]
	v_pk_fma_f32 v[26:27], v[110:111], v[134:135], v[26:27] op_sel_hi:[0,1,1]
	v_pk_fma_f32 v[22:23], v[114:115], v[132:133], v[22:23] op_sel_hi:[0,1,1]
	v_pk_fma_f32 v[18:19], v[114:115], v[134:135], v[18:19] op_sel_hi:[0,1,1]
	v_pk_fma_f32 v[12:13], v[118:119], v[132:133], v[12:13] op_sel_hi:[0,1,1]
	v_pk_fma_f32 v[10:11], v[118:119], v[134:135], v[10:11] op_sel_hi:[0,1,1]
	v_pk_fma_f32 v[8:9], v[122:123], v[132:133], v[8:9] op_sel_hi:[0,1,1]
	v_pk_fma_f32 v[6:7], v[122:123], v[134:135], v[6:7] op_sel_hi:[0,1,1]
	v_pk_fma_f32 v[28:29], v[110:111], v[136:137], v[28:29] op_sel:[1,0,0]
	v_pk_fma_f32 v[26:27], v[110:111], v[138:139], v[26:27] op_sel:[1,0,0]
	v_pk_fma_f32 v[22:23], v[114:115], v[136:137], v[22:23] op_sel:[1,0,0]
	v_pk_fma_f32 v[18:19], v[114:115], v[138:139], v[18:19] op_sel:[1,0,0]
	v_pk_fma_f32 v[12:13], v[118:119], v[136:137], v[12:13] op_sel:[1,0,0]
	v_pk_fma_f32 v[10:11], v[118:119], v[138:139], v[10:11] op_sel:[1,0,0]
	v_pk_fma_f32 v[8:9], v[122:123], v[136:137], v[8:9] op_sel:[1,0,0]
	v_pk_fma_f32 v[6:7], v[122:123], v[138:139], v[6:7] op_sel:[1,0,0]
	v_add_u32_e32 v49, 32, v49
	v_add_u32_e32 v15, 0x880, v15
	s_cmpk_eq_i32 s0, 0x100
	s_cbranch_scc0 .LBB0_644
	v_add_u32_e32 v5, 1, v2
	v_add_u32_e32 v4, v48, v4
	v_lshl_add_u32 v3, v3, 2, v46
	s_mov_b64 s[0:1], 0
